# v27: down-projection sample-row tail split-K reduced from 32-way to 8-way (4x fewer scattered f32 atomics, K=1024 per slice)
# speedup vs baseline: 1.0270x; 1.0249x over previous
; template <int EPI>
; DI void gemm_epilogue(const Params& p, f32x4 (&acc)[8][4], int m0, int n0, int wr, int wc, int fr, int fq, u16* Cb, int ldc) {
;     ...
;         } else if (EPI == EPI_ATOM) {
; #pragma clang loop unroll(full)
;           for (int j = 0; j < 4; ++j) atomicAdd(p.out + O_Y + (size_t)row * 2048 + col + j, v[j]);
; __global__ void __launch_bounds__(NTHREADS) fwd_megakernel(Params p) {
;     ...
;   for (int id = bid; id < 256; id += nb) {
;     const int nt = id & 7, kc = id >> 3;
;     gemm_tile<EPI_ATOM>(p, p.U + kc * 256, DFF, p.WT_DOWN + kc * 256, DFF, 256, (MT / 256 - 1) * 256, nt * 256, smem, nullptr, 0);
.LBB0_2002:
	s_cmpk_gt_i32 s72, 0x3f
	s_cbranch_scc1 .LBB0_2011
	s_waitcnt vmcnt(1)
	v_mov_b32_e32 v161, 0
	s_mov_b64 s[2:3], 0x10000000
	s_brev_b32 s6, 8
	s_mov_b32 s7, 0x10100000
	s_mov_b32 s8, 0x100000
	s_mov_b32 s9, 0x10200000
	s_mov_b32 s10, 0x200000
	s_mov_b32 s11, 0x10300000
	s_mov_b32 s12, 0x300000
	s_mov_b32 s5, 0
	s_branch .LBB0_2005
.LBB0_2004:
	s_waitcnt vmcnt(7)
	v_lshlrev_b32_e32 v121, 6, v160
	s_waitcnt vmcnt(6)
	v_lshl_or_b32 v126, v167, 7, v168
	v_lshlrev_b32_e32 v122, 2, v166
	v_add_u32_e32 v120, 0x4000, v126
	v_or3_b32 v122, v121, v122, s13
	v_ashrrev_i32_e32 v121, 31, v120
	v_lshlrev_b32_e32 v160, 2, v122
	v_add_u32_e32 v122, 0x4010, v126
	v_lshlrev_b64 v[120:121], 13, v[120:121]
	v_ashrrev_i32_e32 v123, 31, v122
	v_add_u32_e32 v124, 0x4020, v126
	v_lshl_add_u64 v[120:121], s[64:65], 0, v[120:121]
	v_lshlrev_b64 v[122:123], 13, v[122:123]
	v_ashrrev_i32_e32 v125, 31, v124
	v_lshl_add_u64 v[120:121], v[120:121], 0, v[160:161]
	v_lshl_add_u64 v[122:123], s[64:65], 0, v[122:123]
	v_lshlrev_b64 v[124:125], 13, v[124:125]
	global_atomic_add_f32 v[120:121], v156, off
	global_atomic_add_f32 v[120:121], v157, off offset:4
	global_atomic_add_f32 v[120:121], v158, off offset:8
	global_atomic_add_f32 v[120:121], v159, off offset:12
	v_lshl_add_u64 v[122:123], v[122:123], 0, v[160:161]
	v_lshl_add_u64 v[124:125], s[64:65], 0, v[124:125]
	global_atomic_add_f32 v[122:123], v140, off
	global_atomic_add_f32 v[122:123], v141, off offset:4
	global_atomic_add_f32 v[122:123], v142, off offset:8
	global_atomic_add_f32 v[122:123], v143, off offset:12
	v_lshl_add_u64 v[124:125], v[124:125], 0, v[160:161]
	global_atomic_add_f32 v[124:125], v116, off
	global_atomic_add_f32 v[124:125], v117, off offset:4
	global_atomic_add_f32 v[124:125], v118, off offset:8
	global_atomic_add_f32 v[124:125], v119, off offset:12
	v_add_u32_e32 v116, 0x4030, v126
	v_ashrrev_i32_e32 v117, 31, v116
	v_lshlrev_b64 v[116:117], 13, v[116:117]
	v_lshl_add_u64 v[116:117], s[64:65], 0, v[116:117]
	v_lshl_add_u64 v[116:117], v[116:117], 0, v[160:161]
	global_atomic_add_f32 v[116:117], v112, off
	global_atomic_add_f32 v[116:117], v113, off offset:4
	global_atomic_add_f32 v[116:117], v114, off offset:8
	global_atomic_add_f32 v[116:117], v115, off offset:12
	v_add_u32_e32 v112, 0x4040, v126
	v_ashrrev_i32_e32 v113, 31, v112
	v_lshlrev_b64 v[112:113], 13, v[112:113]
	v_lshl_add_u64 v[112:113], s[64:65], 0, v[112:113]
	v_lshl_add_u64 v[112:113], v[112:113], 0, v[160:161]
	global_atomic_add_f32 v[112:113], v100, off
	global_atomic_add_f32 v[112:113], v101, off offset:4
	global_atomic_add_f32 v[112:113], v102, off offset:8
	global_atomic_add_f32 v[112:113], v103, off offset:12
	v_add_u32_e32 v100, 0x4050, v126
	v_ashrrev_i32_e32 v101, 31, v100
	v_lshlrev_b64 v[100:101], 13, v[100:101]
	v_lshl_add_u64 v[100:101], s[64:65], 0, v[100:101]
	v_lshl_add_u64 v[100:101], v[100:101], 0, v[160:161]
	global_atomic_add_f32 v[100:101], v88, off
	global_atomic_add_f32 v[100:101], v89, off offset:4
	global_atomic_add_f32 v[100:101], v90, off offset:8
	global_atomic_add_f32 v[100:101], v91, off offset:12
	v_add_u32_e32 v88, 0x4060, v126
	v_ashrrev_i32_e32 v89, 31, v88
	v_lshlrev_b64 v[88:89], 13, v[88:89]
	v_lshl_add_u64 v[88:89], s[64:65], 0, v[88:89]
	v_lshl_add_u64 v[88:89], v[88:89], 0, v[160:161]
	global_atomic_add_f32 v[88:89], v68, off
	global_atomic_add_f32 v[88:89], v69, off offset:4
	global_atomic_add_f32 v[88:89], v70, off offset:8
	global_atomic_add_f32 v[88:89], v71, off offset:12
	v_add_u32_e32 v68, 0x4070, v126
	v_ashrrev_i32_e32 v69, 31, v68
	v_lshlrev_b64 v[68:69], 13, v[68:69]
	v_lshl_add_u64 v[68:69], s[64:65], 0, v[68:69]
	v_lshl_add_u64 v[68:69], v[68:69], 0, v[160:161]
	global_atomic_add_f32 v[68:69], v48, off
	global_atomic_add_f32 v[68:69], v49, off offset:4
	global_atomic_add_f32 v[68:69], v50, off offset:8
	global_atomic_add_f32 v[68:69], v51, off offset:12
	global_atomic_add_f32 v[120:121], v108, off offset:64
	global_atomic_add_f32 v[120:121], v109, off offset:68
	global_atomic_add_f32 v[120:121], v110, off offset:72
	global_atomic_add_f32 v[120:121], v111, off offset:76
	global_atomic_add_f32 v[122:123], v104, off offset:64
	global_atomic_add_f32 v[122:123], v105, off offset:68
	global_atomic_add_f32 v[122:123], v106, off offset:72
	global_atomic_add_f32 v[122:123], v107, off offset:76
	global_atomic_add_f32 v[124:125], v92, off offset:64
	global_atomic_add_f32 v[124:125], v93, off offset:68
	global_atomic_add_f32 v[124:125], v94, off offset:72
	global_atomic_add_f32 v[124:125], v95, off offset:76
	global_atomic_add_f32 v[116:117], v80, off offset:64
	global_atomic_add_f32 v[116:117], v81, off offset:68
	global_atomic_add_f32 v[116:117], v82, off offset:72
	global_atomic_add_f32 v[116:117], v83, off offset:76
	global_atomic_add_f32 v[112:113], v64, off offset:64
	global_atomic_add_f32 v[112:113], v65, off offset:68
	global_atomic_add_f32 v[112:113], v66, off offset:72
	global_atomic_add_f32 v[112:113], v67, off offset:76
	global_atomic_add_f32 v[100:101], v52, off offset:64
	global_atomic_add_f32 v[100:101], v53, off offset:68
	global_atomic_add_f32 v[100:101], v54, off offset:72
	global_atomic_add_f32 v[100:101], v55, off offset:76
	global_atomic_add_f32 v[88:89], v36, off offset:64
	global_atomic_add_f32 v[88:89], v37, off offset:68
	global_atomic_add_f32 v[88:89], v38, off offset:72
	global_atomic_add_f32 v[88:89], v39, off offset:76
	global_atomic_add_f32 v[68:69], v24, off offset:64
	global_atomic_add_f32 v[68:69], v25, off offset:68
	global_atomic_add_f32 v[68:69], v26, off offset:72
	global_atomic_add_f32 v[68:69], v27, off offset:76
; #define G_LOAD(T) { const int k_ = (T) << 6; _Pragma("unroll") for (int i = 0; i < 4; ++i) { \
;     ra[i] = *(const u32x4*)(Ag + (size_t)(i * 64) * lda + k_); rb[i] = *(const u32x4*)(Bg + (size_t)(i * 64) * ldb + k_); } }
; #define L_STORE(ST) { u16* dA_ = sbase + (ST) * GSTAGE + lr * LSTR + lkw; u16* dB_ = dA_ + 256 * LSTR; _Pragma("unroll") for (int i = 0; i < 4; ++i) { \
;     *(u32x4*)(dA_ + i * 64 * LSTR) = ra[i]; *(u32x4*)(dB_ + i * 64 * LSTR) = rb[i]; } }
; template <int EPI>
; DI void gemm_epilogue(const Params& p, f32x4 (&acc)[8][4], int m0, int n0, int wr, int wc, int fr, int fq, u16* Cb, int ldc) {
;     ...
;         } else if (EPI == EPI_ATOM) {
; #pragma clang loop unroll(full)
;           for (int j = 0; j < 4; ++j) atomicAdd(p.out + O_Y + (size_t)row * 2048 + col + j, v[j]);
; template <int EPI>
; DI void gemm_tile(const Params& p, const u16* __restrict__ A, int lda, const u16* __restrict__ Bt, int ldb, int K, int m0, int n0,
;                   char* smem, u16* Cb, int ldc) {
;     ...
;   for (int m = 0; m < 8; ++m)
; #pragma unroll
;     for (int n = 0; n < 4; ++n) acc[m][n] = (f32x4){0.f, 0.f, 0.f, 0.f};
;   const int lr = tid >> 3, lk = (tid & 7) * 8;
;   const int lkw = ((tid & 7) ^ ((lr >> 1) & 7)) * 8;
;   const int fsw = (fr >> 1) & 7, fo0 = (fq ^ fsw) * 8, fo1 = ((4 + fq) ^ fsw) * 8;
;   const u16* Ag = A + (size_t)(m0 + lr) * lda + lk;
;   const u16* Bg = Bt + (size_t)(n0 + lr) * ldb + lk;
;   const int nk = K >> 6;
;   u32x4 ra[4], rb[4];
;     ...
;   G_LOAD(0)
;   L_STORE(0)
;   G_LOAD(1)
	global_atomic_add_f32 v[120:121], v96, off offset:128
	global_atomic_add_f32 v[120:121], v97, off offset:132
	global_atomic_add_f32 v[120:121], v98, off offset:136
	global_atomic_add_f32 v[120:121], v99, off offset:140
	global_atomic_add_f32 v[122:123], v84, off offset:128
	global_atomic_add_f32 v[122:123], v85, off offset:132
	global_atomic_add_f32 v[122:123], v86, off offset:136
	global_atomic_add_f32 v[122:123], v87, off offset:140
	global_atomic_add_f32 v[124:125], v72, off offset:128
	global_atomic_add_f32 v[124:125], v73, off offset:132
	global_atomic_add_f32 v[124:125], v74, off offset:136
	global_atomic_add_f32 v[124:125], v75, off offset:140
	global_atomic_add_f32 v[116:117], v56, off offset:128
	global_atomic_add_f32 v[116:117], v57, off offset:132
	global_atomic_add_f32 v[116:117], v58, off offset:136
	global_atomic_add_f32 v[116:117], v59, off offset:140
	global_atomic_add_f32 v[112:113], v40, off offset:128
	global_atomic_add_f32 v[112:113], v41, off offset:132
	global_atomic_add_f32 v[112:113], v42, off offset:136
	global_atomic_add_f32 v[112:113], v43, off offset:140
	global_atomic_add_f32 v[100:101], v28, off offset:128
	global_atomic_add_f32 v[100:101], v29, off offset:132
	global_atomic_add_f32 v[100:101], v30, off offset:136
	global_atomic_add_f32 v[100:101], v31, off offset:140
	global_atomic_add_f32 v[88:89], v16, off offset:128
	global_atomic_add_f32 v[88:89], v17, off offset:132
	global_atomic_add_f32 v[88:89], v18, off offset:136
	global_atomic_add_f32 v[88:89], v19, off offset:140
	global_atomic_add_f32 v[68:69], v8, off offset:128
	global_atomic_add_f32 v[68:69], v9, off offset:132
	global_atomic_add_f32 v[68:69], v10, off offset:136
	global_atomic_add_f32 v[68:69], v11, off offset:140
	global_atomic_add_f32 v[120:121], v76, off offset:192
	global_atomic_add_f32 v[120:121], v77, off offset:196
	global_atomic_add_f32 v[120:121], v78, off offset:200
	global_atomic_add_f32 v[120:121], v79, off offset:204
	global_atomic_add_f32 v[122:123], v60, off offset:192
	global_atomic_add_f32 v[122:123], v61, off offset:196
	global_atomic_add_f32 v[122:123], v62, off offset:200
	global_atomic_add_f32 v[122:123], v63, off offset:204
	global_atomic_add_f32 v[124:125], v44, off offset:192
	global_atomic_add_f32 v[124:125], v45, off offset:196
	global_atomic_add_f32 v[124:125], v46, off offset:200
	global_atomic_add_f32 v[124:125], v47, off offset:204
	global_atomic_add_f32 v[116:117], v32, off offset:192
	global_atomic_add_f32 v[116:117], v33, off offset:196
	global_atomic_add_f32 v[116:117], v34, off offset:200
	global_atomic_add_f32 v[116:117], v35, off offset:204
	global_atomic_add_f32 v[112:113], v20, off offset:192
	global_atomic_add_f32 v[112:113], v21, off offset:196
	global_atomic_add_f32 v[112:113], v22, off offset:200
	global_atomic_add_f32 v[112:113], v23, off offset:204
	global_atomic_add_f32 v[100:101], v12, off offset:192
	global_atomic_add_f32 v[100:101], v13, off offset:196
	global_atomic_add_f32 v[100:101], v14, off offset:200
	global_atomic_add_f32 v[100:101], v15, off offset:204
	global_atomic_add_f32 v[88:89], v4, off offset:192
	global_atomic_add_f32 v[88:89], v5, off offset:196
	global_atomic_add_f32 v[88:89], v6, off offset:200
	global_atomic_add_f32 v[88:89], v7, off offset:204
	global_atomic_add_f32 v[68:69], v0, off offset:192
	global_atomic_add_f32 v[68:69], v1, off offset:196
	global_atomic_add_f32 v[68:69], v2, off offset:200
	global_atomic_add_f32 v[68:69], v3, off offset:204
	s_add_i32 s72, s72, s73
	s_cmpk_gt_i32 s72, 0x3f
	s_cbranch_scc1 .LBB0_2011
.LBB0_2005:
	s_lshl_b32 s0, s72, 7
	s_and_b32 s0, s0, 0xfffffc00
	s_ashr_i32 s1, s0, 31
	s_lshl_b64 s[0:1], s[0:1], 1
	s_add_u32 s14, s18, s0
	v_mov_b32_e32 v48, v194
	s_addc_u32 s15, s19, s1
	s_add_u32 s0, s20, s0
	v_ashrrev_i32_e32 v32, 3, v48
	v_ashrrev_i32_e32 v33, 31, v32
	s_addc_u32 s1, s21, s1
	s_lshl_b32 s4, s72, 8
	v_lshlrev_b64 v[0:1], 14, v[32:33]
	v_lshlrev_b32_e32 v2, 4, v48
	s_and_b32 s13, s4, 0x700
	v_lshl_add_u64 v[0:1], s[14:15], 0, v[0:1]
	v_and_b32_e32 v160, 0x70, v2
	v_lshl_add_u64 v[34:35], v[0:1], 0, v[160:161]
	v_add_u32_e32 v0, s13, v32
	v_ashrrev_i32_e32 v1, 31, v0
	v_add_co_u32_e32 v12, vcc, s6, v34
	v_lshlrev_b64 v[0:1], 14, v[0:1]
	s_nop 0
	v_addc_co_u32_e32 v13, vcc, 0, v35, vcc
	v_lshl_add_u64 v[0:1], s[0:1], 0, v[0:1]
	v_add_co_u32_e32 v36, vcc, s7, v34
	s_waitcnt vmcnt(0)
	v_lshl_add_u64 v[162:163], v[0:1], 0, v[160:161]
	v_addc_co_u32_e32 v37, vcc, 0, v35, vcc
	v_add_co_u32_e32 v38, vcc, s8, v162
	global_load_dwordx4 v[0:3], v[162:163], off
	s_nop 0
	v_addc_co_u32_e32 v39, vcc, 0, v163, vcc
	v_add_co_u32_e32 v40, vcc, s9, v34
	global_load_dwordx4 v[4:7], v[12:13], off
	global_load_dwordx4 v[8:11], v[36:37], off
	v_addc_co_u32_e32 v41, vcc, 0, v35, vcc
	v_add_co_u32_e32 v42, vcc, s10, v162
	global_load_dwordx4 v[12:15], v[38:39], off
	s_nop 0
	v_addc_co_u32_e32 v43, vcc, 0, v163, vcc
	v_add_co_u32_e32 v44, vcc, s11, v34
	global_load_dwordx4 v[16:19], v[40:41], off
	s_nop 0
	v_addc_co_u32_e32 v45, vcc, 0, v35, vcc
	v_add_co_u32_e32 v46, vcc, s12, v162
	global_load_dwordx4 v[20:23], v[42:43], off
	s_nop 0
	v_addc_co_u32_e32 v47, vcc, 0, v163, vcc
	global_load_dwordx4 v[24:27], v[44:45], off
	global_load_dwordx4 v[28:31], v[46:47], off
	v_lshl_add_u64 v[164:165], v[34:35], 0, s[2:3]
	global_load_dwordx4 v[144:147], v[44:45], off offset:128
	global_load_dwordx4 v[132:135], v[40:41], off offset:128
	global_load_dwordx4 v[128:131], v[36:37], off offset:128
	global_load_dwordx4 v[120:123], v[164:165], off offset:128
	global_load_dwordx4 v[124:127], v[162:163], off offset:128
	global_load_dwordx4 v[152:155], v[46:47], off offset:128
	global_load_dwordx4 v[148:151], v[42:43], off offset:128
	global_load_dwordx4 v[136:139], v[38:39], off offset:128
	v_lshrrev_b32_e32 v33, 4, v48
	v_bfe_u32 v160, v48, 6, 2
	v_ashrrev_i32_e32 v167, 8, v48
	v_bfe_u32 v166, v48, 4, 2
	v_bfe_u32 v49, v48, 1, 3
	v_and_b32_e32 v168, 15, v48
	v_xor_b32_e32 v48, v33, v48
	v_lshlrev_b32_e32 v48, 4, v48
	v_bitop3_b32 v33, v33, v49, 3 bitop3:0x6c
	v_bitop3_b32 v49, v166, v49, 4 bitop3:0x36
	v_lshlrev_b32_e32 v32, 7, v32
	v_and_b32_e32 v48, 0x70, v48
	v_lshlrev_b32_e32 v50, 6, v168
	v_lshlrev_b32_e32 v49, 3, v49
	v_lshlrev_b32_e32 v33, 3, v33
	v_add3_u32 v172, 0, v32, v48
	v_lshlrev_b32_e32 v169, 14, v167
	v_lshlrev_b32_e32 v170, 13, v160
	v_lshlrev_b32_e32 v171, 1, v50
	v_lshlrev_b32_e32 v173, 1, v33
	v_lshlrev_b32_e32 v174, 1, v49
	s_mov_b32 s14, s5
	s_mov_b32 s15, s5
	v_mov_b32_e32 v48, 0
	v_mov_b32_e32 v49, v161
	v_mov_b32_e32 v50, v161
	v_mov_b32_e32 v51, v161
	v_mov_b32_e32 v36, 0
	v_mov_b32_e32 v37, v161
	v_mov_b32_e32 v38, v161
	v_mov_b32_e32 v39, v161
	v_mov_b32_e32 v68, 0
	v_mov_b32_e32 v69, v161
	v_mov_b32_e32 v70, v161
	v_mov_b32_e32 v71, v161
	v_mov_b32_e32 v52, 0
	v_mov_b32_e32 v53, v161
	v_mov_b32_e32 v54, v161
	s_waitcnt vmcnt(14)
; #define G_LOAD(T) { const int k_ = (T) << 6; _Pragma("unroll") for (int i = 0; i < 4; ++i) { \
;     ra[i] = *(const u32x4*)(Ag + (size_t)(i * 64) * lda + k_); rb[i] = *(const u32x4*)(Bg + (size_t)(i * 64) * ldb + k_); } }
; #define L_STORE(ST) { u16* dA_ = sbase + (ST) * GSTAGE + lr * LSTR + lkw; u16* dB_ = dA_ + 256 * LSTR; _Pragma("unroll") for (int i = 0; i < 4; ++i) { \
;     *(u32x4*)(dA_ + i * 64 * LSTR) = ra[i]; *(u32x4*)(dB_ + i * 64 * LSTR) = rb[i]; } }
; template <int EPI>
; DI void gemm_tile(const Params& p, const u16* __restrict__ A, int lda, const u16* __restrict__ Bt, int ldb, int K, int m0, int n0,
;                   char* smem, u16* Cb, int ldc) {
;     ...
;   G_LOAD(0)
;   L_STORE(0)
;   G_LOAD(1)
; #pragma unroll 1
;   for (int kt = 0; kt < nk; ++kt) {
;     __syncthreads();
;     if (kt + 1 < nk) L_STORE((kt + 1) & 1)
;     G_LOAD(min(kt + 2, nk - 1))
;     const u16* cA = sbase + (kt & 1) * GSTAGE + (wr * 128 + fr) * LSTR;
;     const u16* cB = sbase + (kt & 1) * GSTAGE + 256 * LSTR + (wc * 64 + fr) * LSTR;
; #pragma unroll
;     for (int ks = 0; ks < 2; ++ks) {
;       bf16x8 bfr[4];
; #pragma unroll
;       for (int n = 0; n < 4; ++n) bfr[n] = *(const bf16x8*)(cB + n * 16 * LSTR + (ks ? fo1 : fo0));
; #pragma unroll
;       for (int mh = 0; mh < 2; ++mh) {
;         bf16x8 af[4];
; #pragma unroll
;         for (int m = 0; m < 4; ++m) af[m] = *(const bf16x8*)(cA + (mh * 4 + m) * 16 * LSTR + (ks ? fo1 : fo0));
;         __builtin_amdgcn_s_setprio(1);
; #pragma unroll
;         for (int m = 0; m < 4; ++m)
	ds_write_b128 v172, v[4:7]
	s_waitcnt vmcnt(13)
	ds_write_b128 v172, v[8:11] offset:8192
	s_waitcnt vmcnt(11)
	ds_write_b128 v172, v[16:19] offset:16384
	s_waitcnt vmcnt(9)
	ds_write_b128 v172, v[24:27] offset:24576
	ds_write_b128 v172, v[0:3] offset:32768
	ds_write_b128 v172, v[12:15] offset:40960
	ds_write_b128 v172, v[20:23] offset:49152
	s_waitcnt vmcnt(8)
	ds_write_b128 v172, v[28:31] offset:57344
	v_mov_b32_e32 v0, 0
	v_mov_b32_e32 v1, v161
	v_mov_b32_e32 v2, v161
	v_mov_b32_e32 v3, v161
	v_mov_b32_e32 v8, 0
	v_mov_b32_e32 v9, v161
	v_mov_b32_e32 v10, v161
	v_mov_b32_e32 v11, v161
	v_mov_b32_e32 v24, 0
	v_mov_b32_e32 v25, v161
	v_mov_b32_e32 v26, v161
	v_mov_b32_e32 v27, v161
	v_mov_b32_e32 v4, 0
	v_mov_b32_e32 v5, v161
	v_mov_b32_e32 v6, v161
	v_mov_b32_e32 v7, v161
	v_mov_b32_e32 v16, 0
	v_mov_b32_e32 v17, v161
	v_mov_b32_e32 v18, v161
	v_mov_b32_e32 v19, v161
	v_mov_b32_e32 v12, 0
	v_mov_b32_e32 v13, v161
	v_mov_b32_e32 v14, v161
	v_mov_b32_e32 v15, v161
	v_mov_b32_e32 v28, 0
	v_mov_b32_e32 v29, v161
	v_mov_b32_e32 v30, v161
	v_mov_b32_e32 v31, v161
	v_mov_b32_e32 v55, v161
	v_mov_b32_e32 v88, 0
	v_mov_b32_e32 v89, v161
	v_mov_b32_e32 v90, v161
	v_mov_b32_e32 v91, v161
	v_mov_b32_e32 v20, 0
	v_mov_b32_e32 v21, v161
	v_mov_b32_e32 v22, v161
	v_mov_b32_e32 v23, v161
	v_mov_b32_e32 v40, 0
	v_mov_b32_e32 v41, v161
	v_mov_b32_e32 v42, v161
	v_mov_b32_e32 v43, v161
	v_mov_b32_e32 v64, 0
	v_mov_b32_e32 v65, v161
	v_mov_b32_e32 v66, v161
	v_mov_b32_e32 v67, v161
	v_mov_b32_e32 v100, 0
	v_mov_b32_e32 v101, v161
	v_mov_b32_e32 v102, v161
	v_mov_b32_e32 v103, v161
	v_mov_b32_e32 v32, 0
	v_mov_b32_e32 v33, v161
	v_mov_b32_e32 v34, v161
	v_mov_b32_e32 v35, v161
	v_mov_b32_e32 v56, 0
	v_mov_b32_e32 v57, v161
	v_mov_b32_e32 v58, v161
	v_mov_b32_e32 v59, v161
	v_mov_b32_e32 v80, 0
	v_mov_b32_e32 v81, v161
	v_mov_b32_e32 v82, v161
	v_mov_b32_e32 v83, v161
	v_mov_b32_e32 v112, 0
	v_mov_b32_e32 v113, v161
	v_mov_b32_e32 v114, v161
	v_mov_b32_e32 v115, v161
	v_mov_b32_e32 v44, 0
	v_mov_b32_e32 v45, v161
	v_mov_b32_e32 v46, v161
	v_mov_b32_e32 v47, v161
	v_mov_b32_e32 v72, 0
	v_mov_b32_e32 v73, v161
	v_mov_b32_e32 v74, v161
	v_mov_b32_e32 v75, v161
	v_mov_b32_e32 v92, 0
	v_mov_b32_e32 v93, v161
	v_mov_b32_e32 v94, v161
	v_mov_b32_e32 v95, v161
	v_mov_b32_e32 v116, 0
	v_mov_b32_e32 v117, v161
	v_mov_b32_e32 v118, v161
	v_mov_b32_e32 v119, v161
	v_mov_b32_e32 v60, 0
	v_mov_b32_e32 v61, v161
	v_mov_b32_e32 v62, v161
	v_mov_b32_e32 v63, v161
	v_mov_b32_e32 v84, 0
	v_mov_b32_e32 v85, v161
	v_mov_b32_e32 v86, v161
	v_mov_b32_e32 v87, v161
	v_mov_b32_e32 v104, 0
	v_mov_b32_e32 v105, v161
	v_mov_b32_e32 v106, v161
	v_mov_b32_e32 v107, v161
	v_mov_b32_e32 v140, 0
	v_mov_b32_e32 v141, v161
	v_mov_b32_e32 v142, v161
	v_mov_b32_e32 v143, v161
	v_mov_b32_e32 v76, 0
	v_mov_b32_e32 v77, v161
	v_mov_b32_e32 v78, v161
	v_mov_b32_e32 v79, v161
	v_mov_b32_e32 v96, 0
	v_mov_b32_e32 v97, v161
	v_mov_b32_e32 v98, v161
	v_mov_b32_e32 v99, v161
	v_mov_b32_e32 v108, 0
	v_mov_b32_e32 v109, v161
	v_mov_b32_e32 v110, v161
	v_mov_b32_e32 v111, v161
	v_mov_b32_e32 v156, 0
	v_mov_b32_e32 v157, v161
	v_mov_b32_e32 v158, v161
	v_mov_b32_e32 v159, v161
	s_branch .LBB0_2007
.LBB0_2006:
	s_and_b32 s0, s14, 0x8000
	s_lshl_b32 s0, s0, 1
	s_add_i32 s0, s0, 0
	v_add3_u32 v175, s0, v169, v171
	v_add3_u32 v192, s0, v170, v171
	v_add_u32_e32 v188, v192, v173
	v_add_u32_e32 v193, v175, v173
	ds_read_b128 v[176:179], v188 offset:32768
	ds_read_b128 v[180:183], v188 offset:34816
	ds_read_b128 v[184:187], v188 offset:36864
	ds_read_b128 v[188:191], v188 offset:38912
	ds_read_b128 v[196:199], v193
	ds_read_b128 v[200:203], v193 offset:2048
	ds_read_b128 v[204:207], v193 offset:4096
	ds_read_b128 v[208:211], v193 offset:6144
	s_min_i32 s0, s15, 13
	s_lshl_b32 s4, s0, 7
	s_waitcnt vmcnt(0)
	v_lshl_add_u64 v[144:145], v[164:165], 0, s[4:5]
	s_waitcnt vmcnt(5)
	v_add_co_u32_e32 v128, vcc, s8, v144
	s_waitcnt vmcnt(2)
	v_lshl_add_u64 v[152:153], v[162:163], 0, s[4:5]
	v_addc_co_u32_e32 v129, vcc, 0, v145, vcc
	v_add_co_u32_e32 v132, vcc, s8, v152
	global_load_dwordx4 v[120:123], v[144:145], off offset:256
	global_load_dwordx4 v[124:127], v[152:153], off offset:256
	v_addc_co_u32_e32 v133, vcc, 0, v153, vcc
	global_load_dwordx4 v[136:139], v[132:133], off offset:256
	v_add_co_u32_e32 v132, vcc, s10, v144
	global_load_dwordx4 v[128:131], v[128:129], off offset:256
	s_nop 0
	v_addc_co_u32_e32 v133, vcc, 0, v145, vcc
	v_add_co_u32_e32 v146, vcc, s10, v152
	global_load_dwordx4 v[132:135], v[132:133], off offset:256
	s_nop 0
	v_addc_co_u32_e32 v147, vcc, 0, v153, vcc
	v_add_co_u32_e32 v144, vcc, s12, v144
	global_load_dwordx4 v[148:151], v[146:147], off offset:256
	s_nop 0
	v_addc_co_u32_e32 v145, vcc, 0, v145, vcc
	v_add_co_u32_e32 v152, vcc, s12, v152
	s_nop 0
	s_nop 0
	v_addc_co_u32_e32 v153, vcc, 0, v153, vcc
	global_load_dwordx4 v[152:155], v[152:153], off offset:256
	s_nop 0
	global_load_dwordx4 v[144:147], v[144:145], off offset:256
	s_add_i32 s15, s15, 1
	s_setprio 1
	s_waitcnt lgkmcnt(3)
	v_mfma_f32_16x16x32_bf16 v[156:159], v[176:179], v[196:199], v[156:159]
	v_mfma_f32_16x16x32_bf16 v[108:111], v[180:183], v[196:199], v[108:111]
	v_mfma_f32_16x16x32_bf16 v[96:99], v[184:187], v[196:199], v[96:99]
	v_mfma_f32_16x16x32_bf16 v[76:79], v[188:191], v[196:199], v[76:79]
	s_waitcnt lgkmcnt(2)
; #define G_LOAD(T) { const int k_ = (T) << 6; _Pragma("unroll") for (int i = 0; i < 4; ++i) { \
;     ra[i] = *(const u32x4*)(Ag + (size_t)(i * 64) * lda + k_); rb[i] = *(const u32x4*)(Bg + (size_t)(i * 64) * ldb + k_); } }
; #define L_STORE(ST) { u16* dA_ = sbase + (ST) * GSTAGE + lr * LSTR + lkw; u16* dB_ = dA_ + 256 * LSTR; _Pragma("unroll") for (int i = 0; i < 4; ++i) { \
;     *(u32x4*)(dA_ + i * 64 * LSTR) = ra[i]; *(u32x4*)(dB_ + i * 64 * LSTR) = rb[i]; } }
; template <int EPI>
; DI void gemm_tile(const Params& p, const u16* __restrict__ A, int lda, const u16* __restrict__ Bt, int ldb, int K, int m0, int n0,
;                   char* smem, u16* Cb, int ldc) {
;     ...
;   for (int kt = 0; kt < nk; ++kt) {
;     __syncthreads();
;     if (kt + 1 < nk) L_STORE((kt + 1) & 1)
;     G_LOAD(min(kt + 2, nk - 1))
;     const u16* cA = sbase + (kt & 1) * GSTAGE + (wr * 128 + fr) * LSTR;
;     const u16* cB = sbase + (kt & 1) * GSTAGE + 256 * LSTR + (wc * 64 + fr) * LSTR;
; #pragma unroll
;     for (int ks = 0; ks < 2; ++ks) {
;       bf16x8 bfr[4];
; #pragma unroll
;       for (int n = 0; n < 4; ++n) bfr[n] = *(const bf16x8*)(cB + n * 16 * LSTR + (ks ? fo1 : fo0));
; #pragma unroll
;       for (int mh = 0; mh < 2; ++mh) {
;         bf16x8 af[4];
; #pragma unroll
;         for (int m = 0; m < 4; ++m) af[m] = *(const bf16x8*)(cA + (mh * 4 + m) * 16 * LSTR + (ks ? fo1 : fo0));
;         __builtin_amdgcn_s_setprio(1);
; #pragma unroll
;         for (int m = 0; m < 4; ++m)
; #pragma unroll
;           for (int n = 0; n < 4; ++n)
;             acc[mh * 4 + m][n] = EpiSwap<EPI>::v ? __builtin_amdgcn_mfma_f32_16x16x32_bf16(bfr[n], af[m], acc[mh * 4 + m][n], 0, 0, 0)
;                                                  : __builtin_amdgcn_mfma_f32_16x16x32_bf16(af[m], bfr[n], acc[mh * 4 + m][n], 0, 0, 0);
;         __builtin_amdgcn_s_setprio(0);
;       }
;     }
;   }
	v_mfma_f32_16x16x32_bf16 v[140:143], v[176:179], v[200:203], v[140:143]
	v_mfma_f32_16x16x32_bf16 v[104:107], v[180:183], v[200:203], v[104:107]
	v_mfma_f32_16x16x32_bf16 v[84:87], v[184:187], v[200:203], v[84:87]
	v_mfma_f32_16x16x32_bf16 v[60:63], v[188:191], v[200:203], v[60:63]
	s_waitcnt lgkmcnt(1)
	v_mfma_f32_16x16x32_bf16 v[116:119], v[176:179], v[204:207], v[116:119]
	v_mfma_f32_16x16x32_bf16 v[92:95], v[180:183], v[204:207], v[92:95]
	v_mfma_f32_16x16x32_bf16 v[72:75], v[184:187], v[204:207], v[72:75]
	v_mfma_f32_16x16x32_bf16 v[44:47], v[188:191], v[204:207], v[44:47]
	s_waitcnt lgkmcnt(0)
	v_mfma_f32_16x16x32_bf16 v[112:115], v[176:179], v[208:211], v[112:115]
	v_mfma_f32_16x16x32_bf16 v[80:83], v[180:183], v[208:211], v[80:83]
	v_mfma_f32_16x16x32_bf16 v[56:59], v[184:187], v[208:211], v[56:59]
	v_mfma_f32_16x16x32_bf16 v[32:35], v[188:191], v[208:211], v[32:35]
	s_setprio 0
	ds_read_b128 v[196:199], v193 offset:8192
	ds_read_b128 v[200:203], v193 offset:10240
	ds_read_b128 v[204:207], v193 offset:12288
	ds_read_b128 v[208:211], v193 offset:14336
	s_setprio 1
	s_waitcnt lgkmcnt(3)
	v_mfma_f32_16x16x32_bf16 v[100:103], v[176:179], v[196:199], v[100:103]
	v_mfma_f32_16x16x32_bf16 v[64:67], v[180:183], v[196:199], v[64:67]
	v_mfma_f32_16x16x32_bf16 v[40:43], v[184:187], v[196:199], v[40:43]
	v_mfma_f32_16x16x32_bf16 v[20:23], v[188:191], v[196:199], v[20:23]
	s_waitcnt lgkmcnt(2)
	v_mfma_f32_16x16x32_bf16 v[88:91], v[176:179], v[200:203], v[88:91]
	v_mfma_f32_16x16x32_bf16 v[52:55], v[180:183], v[200:203], v[52:55]
	v_mfma_f32_16x16x32_bf16 v[28:31], v[184:187], v[200:203], v[28:31]
	v_mfma_f32_16x16x32_bf16 v[12:15], v[188:191], v[200:203], v[12:15]
	s_waitcnt lgkmcnt(1)
	v_mfma_f32_16x16x32_bf16 v[68:71], v[176:179], v[204:207], v[68:71]
	v_mfma_f32_16x16x32_bf16 v[36:39], v[180:183], v[204:207], v[36:39]
	v_mfma_f32_16x16x32_bf16 v[16:19], v[184:187], v[204:207], v[16:19]
	v_mfma_f32_16x16x32_bf16 v[4:7], v[188:191], v[204:207], v[4:7]
	s_waitcnt lgkmcnt(0)
	v_mfma_f32_16x16x32_bf16 v[48:51], v[176:179], v[208:211], v[48:51]
	v_mfma_f32_16x16x32_bf16 v[24:27], v[180:183], v[208:211], v[24:27]
	v_mfma_f32_16x16x32_bf16 v[8:11], v[184:187], v[208:211], v[8:11]
	v_mfma_f32_16x16x32_bf16 v[0:3], v[188:191], v[208:211], v[0:3]
	s_setprio 0
	v_add_u32_e32 v188, v192, v174
	v_add_u32_e32 v175, v175, v174
	ds_read_b128 v[176:179], v188 offset:32768
	ds_read_b128 v[180:183], v188 offset:34816
	ds_read_b128 v[184:187], v188 offset:36864
	ds_read_b128 v[188:191], v188 offset:38912
	ds_read_b128 v[196:199], v175
	ds_read_b128 v[200:203], v175 offset:2048
	ds_read_b128 v[204:207], v175 offset:4096
	ds_read_b128 v[208:211], v175 offset:6144
	s_setprio 1
	s_waitcnt lgkmcnt(3)
	v_mfma_f32_16x16x32_bf16 v[156:159], v[176:179], v[196:199], v[156:159]
	v_mfma_f32_16x16x32_bf16 v[108:111], v[180:183], v[196:199], v[108:111]
	v_mfma_f32_16x16x32_bf16 v[96:99], v[184:187], v[196:199], v[96:99]
	v_mfma_f32_16x16x32_bf16 v[76:79], v[188:191], v[196:199], v[76:79]
	s_waitcnt lgkmcnt(2)
	v_mfma_f32_16x16x32_bf16 v[140:143], v[176:179], v[200:203], v[140:143]
	v_mfma_f32_16x16x32_bf16 v[104:107], v[180:183], v[200:203], v[104:107]
	v_mfma_f32_16x16x32_bf16 v[84:87], v[184:187], v[200:203], v[84:87]
	v_mfma_f32_16x16x32_bf16 v[60:63], v[188:191], v[200:203], v[60:63]
	s_waitcnt lgkmcnt(1)
	v_mfma_f32_16x16x32_bf16 v[116:119], v[176:179], v[204:207], v[116:119]
	v_mfma_f32_16x16x32_bf16 v[92:95], v[180:183], v[204:207], v[92:95]
	v_mfma_f32_16x16x32_bf16 v[72:75], v[184:187], v[204:207], v[72:75]
	v_mfma_f32_16x16x32_bf16 v[44:47], v[188:191], v[204:207], v[44:47]
	s_waitcnt lgkmcnt(0)
	v_mfma_f32_16x16x32_bf16 v[112:115], v[176:179], v[208:211], v[112:115]
	v_mfma_f32_16x16x32_bf16 v[80:83], v[180:183], v[208:211], v[80:83]
	v_mfma_f32_16x16x32_bf16 v[56:59], v[184:187], v[208:211], v[56:59]
	v_mfma_f32_16x16x32_bf16 v[32:35], v[188:191], v[208:211], v[32:35]
	s_setprio 0
	ds_read_b128 v[196:199], v175 offset:8192
	ds_read_b128 v[200:203], v175 offset:10240
	ds_read_b128 v[204:207], v175 offset:12288
	ds_read_b128 v[208:211], v175 offset:14336
	s_setprio 1
	s_waitcnt lgkmcnt(3)
	v_mfma_f32_16x16x32_bf16 v[100:103], v[176:179], v[196:199], v[100:103]
	v_mfma_f32_16x16x32_bf16 v[64:67], v[180:183], v[196:199], v[64:67]
	v_mfma_f32_16x16x32_bf16 v[40:43], v[184:187], v[196:199], v[40:43]
	v_mfma_f32_16x16x32_bf16 v[20:23], v[188:191], v[196:199], v[20:23]
	s_waitcnt lgkmcnt(2)
	v_mfma_f32_16x16x32_bf16 v[88:91], v[176:179], v[200:203], v[88:91]
	v_mfma_f32_16x16x32_bf16 v[52:55], v[180:183], v[200:203], v[52:55]
	v_mfma_f32_16x16x32_bf16 v[28:31], v[184:187], v[200:203], v[28:31]
	v_mfma_f32_16x16x32_bf16 v[12:15], v[188:191], v[200:203], v[12:15]
	s_waitcnt lgkmcnt(1)
	v_mfma_f32_16x16x32_bf16 v[68:71], v[176:179], v[204:207], v[68:71]
	v_mfma_f32_16x16x32_bf16 v[36:39], v[180:183], v[204:207], v[36:39]
	v_mfma_f32_16x16x32_bf16 v[16:19], v[184:187], v[204:207], v[16:19]
	v_mfma_f32_16x16x32_bf16 v[4:7], v[188:191], v[204:207], v[4:7]
	s_waitcnt lgkmcnt(0)
	v_mfma_f32_16x16x32_bf16 v[48:51], v[176:179], v[208:211], v[48:51]
	v_mfma_f32_16x16x32_bf16 v[24:27], v[180:183], v[208:211], v[24:27]
	v_mfma_f32_16x16x32_bf16 v[8:11], v[184:187], v[208:211], v[8:11]
	v_mfma_f32_16x16x32_bf16 v[0:3], v[188:191], v[208:211], v[0:3]
	s_setprio 0
	s_cmp_lg_u32 s15, 16
	s_mov_b32 s14, s16
	s_cbranch_scc0 .LBB0_2004
.LBB0_2007:
	s_cmp_lt_u32 s15, 15
	s_mov_b64 s[0:1], -1
	s_waitcnt lgkmcnt(0)
	s_barrier
	s_cbranch_scc1 .LBB0_2009
	s_add_i32 s16, s14, 0x8000
	s_mov_b64 s[0:1], 0
